# FFN-out sample-row unit k-loop fully unrolled: 24 fragment loads in flight then 6 more behind the MFMAs (was 5 dependent round trips)
# baseline (speedup 1.0000x reference)
; template <int NB>
; __device__ __forceinline__ void small_core(LAS unsigned char* lds, const bf16_t* A, int lda, const bf16_t* B0, const bf16_t* B1, int K, f32x4 (&out)[NB]) {
;     ...
;     for (; st + 8 < nsteps; st += 16) {
;         const int k = st * 32, k2 = k + 256;
;         bf16x8 b[NB], b2[NB]; b[0] = *(const bf16x8*)(bp0 + k); b2[0] = *(const bf16x8*)(bp0 + k2);
;         if (NB == 2) { b[NB - 1] = *(const bf16x8*)(bp1 + k); b2[NB - 1] = *(const bf16x8*)(bp1 + k2); }
;         bf16x8 a[8], a2[8];
; #pragma unroll
;         for (int mb = 0; mb < 8; ++mb) { a[mb] = *(const bf16x8*)(ap + (size_t)(16 * mb) * lda + k); a2[mb] = *(const bf16x8*)(ap + (size_t)(16 * mb) * lda + k2); }
; #pragma unroll
;         for (int mb = 0; mb < 8; ++mb)
; #pragma unroll
;             for (int nb = 0; nb < NB; ++nb) { acc[nb][mb] = __builtin_amdgcn_mfma_f32_16x16x32_bf16(b[nb], a[mb], acc[nb][mb], 0, 0, 0);
;                 acc[nb][mb] = __builtin_amdgcn_mfma_f32_16x16x32_bf16(b2[nb], a2[mb], acc[nb][mb], 0, 0, 0); }
;     }
.LBB0_332:
	s_ashr_i32 s11, s10, 31
	s_lshl_b64 s[20:21], s[10:11], 1
	v_lshl_add_u64 v[80:81], v[48:49], 0, s[20:21]
	v_lshl_add_u64 v[82:83], v[46:47], 0, s[20:21]
	v_lshl_add_u64 v[84:85], v[50:51], 0, s[20:21]
	global_load_dwordx4 v[104:107], v[80:81], off
	global_load_dwordx4 v[108:111], v[82:83], off
	global_load_dwordx4 v[112:115], v[84:85], off
	global_load_dwordx4 v[154:157], v[80:81], off offset:512
	global_load_dwordx4 v[162:165], v[82:83], off offset:512
	global_load_dwordx4 v[172:175], v[84:85], off offset:512
	global_load_dwordx4 v[74:77], v[80:81], off offset:1024
	global_load_dwordx4 v[116:119], v[82:83], off offset:1024
	global_load_dwordx4 v[120:123], v[84:85], off offset:1024
	global_load_dwordx4 v[124:127], v[80:81], off offset:1536
	global_load_dwordx4 v[128:131], v[82:83], off offset:1536
	global_load_dwordx4 v[144:147], v[84:85], off offset:1536
	global_load_dwordx4 v[150:153], v[80:81], off offset:2048
	global_load_dwordx4 v[182:185], v[82:83], off offset:2048
	global_load_dwordx4 v[186:189], v[84:85], off offset:2048
	global_load_dwordx4 v[190:193], v[80:81], off offset:2560
	global_load_dwordx4 v[194:197], v[82:83], off offset:2560
	global_load_dwordx4 v[198:201], v[84:85], off offset:2560
	global_load_dwordx4 v[202:205], v[80:81], off offset:3072
	global_load_dwordx4 v[206:209], v[82:83], off offset:3072
	global_load_dwordx4 v[210:213], v[84:85], off offset:3072
	global_load_dwordx4 v[214:217], v[80:81], off offset:3584
	global_load_dwordx4 v[218:221], v[82:83], off offset:3584
	global_load_dwordx4 v[222:225], v[84:85], off offset:3584
	s_mov_b32 s100, 0x1000
	s_mov_b32 s101, 0
	v_lshl_add_u64 v[80:81], v[80:81], 0, s[100:101]
	v_lshl_add_u64 v[82:83], v[82:83], 0, s[100:101]
	v_lshl_add_u64 v[84:85], v[84:85], 0, s[100:101]
	s_add_i32 s4, s4, 0x50
	s_waitcnt vmcnt(0)
	v_mfma_f32_16x16x32_bf16 v[28:31], v[104:107], v[108:111], v[28:31]
	v_mfma_f32_16x16x32_bf16 v[24:27], v[104:107], v[112:115], v[24:27]
	v_mfma_f32_16x16x32_bf16 v[28:31], v[154:157], v[162:165], v[28:31]
	v_mfma_f32_16x16x32_bf16 v[24:27], v[154:157], v[172:175], v[24:27]
	global_load_dwordx4 v[104:107], v[80:81], off
	global_load_dwordx4 v[108:111], v[82:83], off
	global_load_dwordx4 v[112:115], v[84:85], off
	global_load_dwordx4 v[154:157], v[80:81], off offset:512
	global_load_dwordx4 v[162:165], v[82:83], off offset:512
	global_load_dwordx4 v[172:175], v[84:85], off offset:512
	v_mfma_f32_16x16x32_bf16 v[28:31], v[74:77], v[116:119], v[28:31]
	v_mfma_f32_16x16x32_bf16 v[24:27], v[74:77], v[120:123], v[24:27]
	v_mfma_f32_16x16x32_bf16 v[28:31], v[124:127], v[128:131], v[28:31]
	v_mfma_f32_16x16x32_bf16 v[24:27], v[124:127], v[144:147], v[24:27]
	v_mfma_f32_16x16x32_bf16 v[28:31], v[150:153], v[182:185], v[28:31]
	v_mfma_f32_16x16x32_bf16 v[24:27], v[150:153], v[186:189], v[24:27]
	v_mfma_f32_16x16x32_bf16 v[28:31], v[190:193], v[194:197], v[28:31]
	v_mfma_f32_16x16x32_bf16 v[24:27], v[190:193], v[198:201], v[24:27]
	v_mfma_f32_16x16x32_bf16 v[28:31], v[202:205], v[206:209], v[28:31]
	v_mfma_f32_16x16x32_bf16 v[24:27], v[202:205], v[210:213], v[24:27]
	v_mfma_f32_16x16x32_bf16 v[28:31], v[214:217], v[218:221], v[28:31]
	v_mfma_f32_16x16x32_bf16 v[24:27], v[214:217], v[222:225], v[24:27]
	s_waitcnt vmcnt(0)
	v_mfma_f32_16x16x32_bf16 v[28:31], v[104:107], v[108:111], v[28:31]
	v_mfma_f32_16x16x32_bf16 v[24:27], v[104:107], v[112:115], v[24:27]
	v_mfma_f32_16x16x32_bf16 v[28:31], v[154:157], v[162:165], v[28:31]
	v_mfma_f32_16x16x32_bf16 v[24:27], v[154:157], v[172:175], v[24:27]

; template <int NB>
; __device__ __forceinline__ void small_core(LAS unsigned char* lds, const bf16_t* A, int lda, const bf16_t* B0, const bf16_t* B1, int K, f32x4 (&out)[NB]) {
;     ...
;     for (; st + 8 < nsteps; st += 16) {
;         const int k = st * 32, k2 = k + 256;
;         bf16x8 b[NB], b2[NB]; b[0] = *(const bf16x8*)(bp0 + k); b2[0] = *(const bf16x8*)(bp0 + k2);
;         if (NB == 2) { b[NB - 1] = *(const bf16x8*)(bp1 + k); b2[NB - 1] = *(const bf16x8*)(bp1 + k2); }
;         bf16x8 a[8], a2[8];
; #pragma unroll
;         for (int mb = 0; mb < 8; ++mb) { a[mb] = *(const bf16x8*)(ap + (size_t)(16 * mb) * lda + k); a2[mb] = *(const bf16x8*)(ap + (size_t)(16 * mb) * lda + k2); }
; #pragma unroll
;         for (int mb = 0; mb < 8; ++mb)
; #pragma unroll
;             for (int nb = 0; nb < NB; ++nb) { acc[nb][mb] = __builtin_amdgcn_mfma_f32_16x16x32_bf16(b[nb], a[mb], acc[nb][mb], 0, 0, 0);
;                 acc[nb][mb] = __builtin_amdgcn_mfma_f32_16x16x32_bf16(b2[nb], a2[mb], acc[nb][mb], 0, 0, 0); }
;     }
.LBB0_1061:
	s_ashr_i32 s53, s52, 31
	s_lshl_b64 s[56:57], s[52:53], 1
	v_lshl_add_u64 v[100:101], v[48:49], 0, s[56:57]
	v_lshl_add_u64 v[108:109], v[46:47], 0, s[56:57]
	v_lshl_add_u64 v[112:113], v[50:51], 0, s[56:57]
	global_load_dwordx4 v[126:129], v[100:101], off
	global_load_dwordx4 v[130:133], v[108:109], off
	global_load_dwordx4 v[142:145], v[112:113], off
	global_load_dwordx4 v[166:169], v[100:101], off offset:512
	global_load_dwordx4 v[194:197], v[108:109], off offset:512
	global_load_dwordx4 v[198:201], v[112:113], off offset:512
	global_load_dwordx4 v[74:77], v[100:101], off offset:1024
	global_load_dwordx4 v[82:85], v[108:109], off offset:1024
	global_load_dwordx4 v[86:89], v[112:113], off offset:1024
	global_load_dwordx4 v[90:93], v[100:101], off offset:1536
	global_load_dwordx4 v[94:97], v[108:109], off offset:1536
	global_load_dwordx4 v[104:107], v[112:113], off offset:1536
	global_load_dwordx4 v[146:149], v[100:101], off offset:2048
	global_load_dwordx4 v[150:153], v[108:109], off offset:2048
	global_load_dwordx4 v[154:157], v[112:113], off offset:2048
	global_load_dwordx4 v[158:161], v[100:101], off offset:2560
	global_load_dwordx4 v[162:165], v[108:109], off offset:2560
	global_load_dwordx4 v[170:173], v[112:113], off offset:2560
	global_load_dwordx4 v[202:205], v[100:101], off offset:3072
	global_load_dwordx4 v[206:209], v[108:109], off offset:3072
	global_load_dwordx4 v[210:213], v[112:113], off offset:3072
	global_load_dwordx4 v[214:217], v[100:101], off offset:3584
	global_load_dwordx4 v[218:221], v[108:109], off offset:3584
	global_load_dwordx4 v[222:225], v[112:113], off offset:3584
	s_mov_b32 s100, 0x1000
	s_mov_b32 s101, 0
	v_lshl_add_u64 v[100:101], v[100:101], 0, s[100:101]
	v_lshl_add_u64 v[108:109], v[108:109], 0, s[100:101]
	v_lshl_add_u64 v[112:113], v[112:113], 0, s[100:101]
	s_add_i32 s4, s4, 0x50
	s_waitcnt vmcnt(0)
	v_mfma_f32_16x16x32_bf16 v[28:31], v[126:129], v[130:133], v[28:31]
	v_mfma_f32_16x16x32_bf16 v[24:27], v[126:129], v[142:145], v[24:27]
	v_mfma_f32_16x16x32_bf16 v[28:31], v[166:169], v[194:197], v[28:31]
	v_mfma_f32_16x16x32_bf16 v[24:27], v[166:169], v[198:201], v[24:27]
	global_load_dwordx4 v[126:129], v[100:101], off
	global_load_dwordx4 v[130:133], v[108:109], off
	global_load_dwordx4 v[142:145], v[112:113], off
	global_load_dwordx4 v[166:169], v[100:101], off offset:512
	global_load_dwordx4 v[194:197], v[108:109], off offset:512
	global_load_dwordx4 v[198:201], v[112:113], off offset:512
	v_mfma_f32_16x16x32_bf16 v[28:31], v[74:77], v[82:85], v[28:31]
	v_mfma_f32_16x16x32_bf16 v[24:27], v[74:77], v[86:89], v[24:27]
	v_mfma_f32_16x16x32_bf16 v[28:31], v[90:93], v[94:97], v[28:31]
	v_mfma_f32_16x16x32_bf16 v[24:27], v[90:93], v[104:107], v[24:27]
	v_mfma_f32_16x16x32_bf16 v[28:31], v[146:149], v[150:153], v[28:31]
	v_mfma_f32_16x16x32_bf16 v[24:27], v[146:149], v[154:157], v[24:27]
	v_mfma_f32_16x16x32_bf16 v[28:31], v[158:161], v[162:165], v[28:31]
	v_mfma_f32_16x16x32_bf16 v[24:27], v[158:161], v[170:173], v[24:27]
	v_mfma_f32_16x16x32_bf16 v[28:31], v[202:205], v[206:209], v[28:31]
	v_mfma_f32_16x16x32_bf16 v[24:27], v[202:205], v[210:213], v[24:27]
	v_mfma_f32_16x16x32_bf16 v[28:31], v[214:217], v[218:221], v[28:31]
	v_mfma_f32_16x16x32_bf16 v[24:27], v[214:217], v[222:225], v[24:27]
	s_waitcnt vmcnt(0)
	v_mfma_f32_16x16x32_bf16 v[28:31], v[126:129], v[130:133], v[28:31]
	v_mfma_f32_16x16x32_bf16 v[24:27], v[126:129], v[142:145], v[24:27]
	v_mfma_f32_16x16x32_bf16 v[28:31], v[166:169], v[194:197], v[28:31]
	v_mfma_f32_16x16x32_bf16 v[24:27], v[166:169], v[198:201], v[24:27]

; template <int NB>
; __device__ __forceinline__ void small_core(LAS unsigned char* lds, const bf16_t* A, int lda, const bf16_t* B0, const bf16_t* B1, int K, f32x4 (&out)[NB]) {
;     ...
;     for (; st + 8 < nsteps; st += 16) {
;         const int k = st * 32, k2 = k + 256;
;         bf16x8 b[NB], b2[NB]; b[0] = *(const bf16x8*)(bp0 + k); b2[0] = *(const bf16x8*)(bp0 + k2);
;         if (NB == 2) { b[NB - 1] = *(const bf16x8*)(bp1 + k); b2[NB - 1] = *(const bf16x8*)(bp1 + k2); }
;         bf16x8 a[8], a2[8];
; #pragma unroll
;         for (int mb = 0; mb < 8; ++mb) { a[mb] = *(const bf16x8*)(ap + (size_t)(16 * mb) * lda + k); a2[mb] = *(const bf16x8*)(ap + (size_t)(16 * mb) * lda + k2); }
; #pragma unroll
;         for (int mb = 0; mb < 8; ++mb)
; #pragma unroll
;             for (int nb = 0; nb < NB; ++nb) { acc[nb][mb] = __builtin_amdgcn_mfma_f32_16x16x32_bf16(b[nb], a[mb], acc[nb][mb], 0, 0, 0);
;                 acc[nb][mb] = __builtin_amdgcn_mfma_f32_16x16x32_bf16(b2[nb], a2[mb], acc[nb][mb], 0, 0, 0); }
;     }
.LBB0_1786:
	s_ashr_i32 s29, s28, 31
	s_lshl_b64 s[34:35], s[28:29], 1
	v_lshl_add_u64 v[98:99], v[48:49], 0, s[34:35]
	v_lshl_add_u64 v[106:107], v[46:47], 0, s[34:35]
	v_lshl_add_u64 v[110:111], v[50:51], 0, s[34:35]
	global_load_dwordx4 v[124:127], v[98:99], off
	global_load_dwordx4 v[128:131], v[106:107], off
	global_load_dwordx4 v[132:135], v[110:111], off
	global_load_dwordx4 v[156:159], v[98:99], off offset:512
	global_load_dwordx4 v[164:167], v[106:107], off offset:512
	global_load_dwordx4 v[168:171], v[110:111], off offset:512
	global_load_dwordx4 v[72:75], v[98:99], off offset:1024
	global_load_dwordx4 v[76:79], v[106:107], off offset:1024
	global_load_dwordx4 v[80:83], v[110:111], off offset:1024
	global_load_dwordx4 v[84:87], v[98:99], off offset:1536
	global_load_dwordx4 v[88:91], v[106:107], off offset:1536
	global_load_dwordx4 v[92:95], v[110:111], off offset:1536
	global_load_dwordx4 v[100:103], v[98:99], off offset:2048
	global_load_dwordx4 v[136:139], v[106:107], off offset:2048
	global_load_dwordx4 v[140:143], v[110:111], off offset:2048
	global_load_dwordx4 v[144:147], v[98:99], off offset:2560
	global_load_dwordx4 v[148:151], v[106:107], off offset:2560
	global_load_dwordx4 v[152:155], v[110:111], off offset:2560
	global_load_dwordx4 v[160:163], v[98:99], off offset:3072
	global_load_dwordx4 v[172:175], v[106:107], off offset:3072
	global_load_dwordx4 v[182:185], v[110:111], off offset:3072
	global_load_dwordx4 v[186:189], v[98:99], off offset:3584
	global_load_dwordx4 v[190:193], v[106:107], off offset:3584
	global_load_dwordx4 v[194:197], v[110:111], off offset:3584
	s_mov_b32 s100, 0x1000
	s_mov_b32 s101, 0
	v_lshl_add_u64 v[98:99], v[98:99], 0, s[100:101]
	v_lshl_add_u64 v[106:107], v[106:107], 0, s[100:101]
	v_lshl_add_u64 v[110:111], v[110:111], 0, s[100:101]
	s_add_i32 s6, s6, 0x50
	s_waitcnt vmcnt(0)
	v_mfma_f32_16x16x32_bf16 v[28:31], v[124:127], v[128:131], v[28:31]
	v_mfma_f32_16x16x32_bf16 v[24:27], v[124:127], v[132:135], v[24:27]
	v_mfma_f32_16x16x32_bf16 v[28:31], v[156:159], v[164:167], v[28:31]
	v_mfma_f32_16x16x32_bf16 v[24:27], v[156:159], v[168:171], v[24:27]
	global_load_dwordx4 v[124:127], v[98:99], off
	global_load_dwordx4 v[128:131], v[106:107], off
	global_load_dwordx4 v[132:135], v[110:111], off
	global_load_dwordx4 v[156:159], v[98:99], off offset:512
	global_load_dwordx4 v[164:167], v[106:107], off offset:512
	global_load_dwordx4 v[168:171], v[110:111], off offset:512
	v_mfma_f32_16x16x32_bf16 v[28:31], v[72:75], v[76:79], v[28:31]
	v_mfma_f32_16x16x32_bf16 v[24:27], v[72:75], v[80:83], v[24:27]
	v_mfma_f32_16x16x32_bf16 v[28:31], v[84:87], v[88:91], v[28:31]
	v_mfma_f32_16x16x32_bf16 v[24:27], v[84:87], v[92:95], v[24:27]
	v_mfma_f32_16x16x32_bf16 v[28:31], v[100:103], v[136:139], v[28:31]
	v_mfma_f32_16x16x32_bf16 v[24:27], v[100:103], v[140:143], v[24:27]
	v_mfma_f32_16x16x32_bf16 v[28:31], v[144:147], v[148:151], v[28:31]
	v_mfma_f32_16x16x32_bf16 v[24:27], v[144:147], v[152:155], v[24:27]
	v_mfma_f32_16x16x32_bf16 v[28:31], v[160:163], v[172:175], v[28:31]
	v_mfma_f32_16x16x32_bf16 v[24:27], v[160:163], v[182:185], v[24:27]
	v_mfma_f32_16x16x32_bf16 v[28:31], v[186:189], v[190:193], v[28:31]
	v_mfma_f32_16x16x32_bf16 v[24:27], v[186:189], v[194:197], v[24:27]
	s_waitcnt vmcnt(0)
	v_mfma_f32_16x16x32_bf16 v[28:31], v[124:127], v[128:131], v[28:31]
	v_mfma_f32_16x16x32_bf16 v[24:27], v[124:127], v[132:135], v[24:27]
	v_mfma_f32_16x16x32_bf16 v[28:31], v[156:159], v[164:167], v[28:31]
	v_mfma_f32_16x16x32_bf16 v[24:27], v[156:159], v[168:171], v[24:27]
